# S5 tile loop: dropped the full LDS drains between a wave's own LDS writes and its reads of them (LDS ops of one wave execute in order; counted waits still cover the register results)
# speedup vs baseline: 1.0039x; 1.0039x over previous
.LBB0_324:
	v_lshlrev_b32_e32 v6, 16, v0
	v_and_b32_e32 v7, 0xffff0000, v0
	v_lshlrev_b32_e32 v0, 16, v1
	v_and_b32_e32 v1, 0xffff0000, v1
	s_waitcnt vmcnt(0)
	v_pk_fma_f32 v[116:117], v[4:5], v[0:1], v[70:71] op_sel_hi:[0,1,1]
	v_lshlrev_b32_e32 v0, 16, v2
	v_and_b32_e32 v1, 0xffff0000, v2
	v_pk_fma_f32 v[118:119], v[4:5], v[0:1], v[64:65] op_sel_hi:[0,1,1]
	v_lshlrev_b32_e32 v0, 16, v3
	v_and_b32_e32 v1, 0xffff0000, v3
	v_pk_fma_f32 v[114:115], v[4:5], v[6:7], v[68:69] op_sel_hi:[0,1,1]
	v_pk_fma_f32 v[120:121], v[4:5], v[0:1], v[66:67] op_sel_hi:[0,1,1]
	v_cvt_pk_bf16_f32 v122, v114, v115
	v_cvt_pk_bf16_f32 v123, v116, v117
	v_cvt_pk_bf16_f32 v124, v118, v119
	v_cvt_pk_bf16_f32 v125, v120, v121
	s_mov_b64 s[22:23], 0x1000
	v_lshl_add_u64 v[94:95], v[94:95], 0, s[22:23]
	v_mfma_f32_32x32x16_bf16 v[16:31], v[122:125], v[32:35], 0
	v_mfma_f32_32x32x16_bf16 v[0:15], v[122:125], v[36:39], 0
	ds_write_b128 v102, v[114:117] offset:27136
	ds_write_b128 v102, v[118:121] offset:27152
	s_nop 8
	ds_write_b128 v106, v[16:19]
	ds_write_b128 v106, v[20:23] offset:32
	ds_write_b128 v106, v[24:27] offset:64
	ds_write_b128 v106, v[28:31] offset:96
	ds_write_b128 v106, v[0:3] offset:4608
	v_mfma_f32_32x32x16_bf16 v[16:31], v[122:125], v[40:43], 0
	ds_write_b128 v106, v[4:7] offset:4640
	ds_write_b128 v106, v[8:11] offset:4672
	ds_write_b128 v106, v[12:15] offset:4704
	s_nop 8
	ds_write_b128 v106, v[16:19] offset:9216
	ds_write_b128 v106, v[20:23] offset:9248
	ds_write_b128 v106, v[24:27] offset:9280
	ds_write_b128 v106, v[28:31] offset:9312
	v_mfma_f32_32x32x16_bf16 v[0:15], v[122:125], v[44:47], 0
	s_nop 11
	ds_write_b128 v106, v[0:3] offset:13824
	ds_write_b128 v106, v[4:7] offset:13856
	ds_write_b128 v106, v[8:11] offset:13888
	ds_write_b128 v106, v[12:15] offset:13920
	ds_read_b128 v[4:7], v107 offset:9216
	ds_read_b128 v[114:117], v107 offset:9232
	ds_read_b128 v[12:15], v107
	ds_read_b128 v[118:121], v107 offset:16
	ds_read_b128 v[122:125], v107 offset:32
	ds_read_b128 v[126:129], v107 offset:48
	ds_read_b128 v[130:133], v107 offset:9248
	ds_read_b128 v[134:137], v107 offset:9264
	ds_read_b128 v[28:31], v107 offset:64
	ds_read_b128 v[20:23], v107 offset:80
	ds_read_b128 v[24:27], v107 offset:9280
	ds_read_b128 v[16:19], v107 offset:9296
	ds_read_b128 v[8:11], v107 offset:96
	ds_read_b128 v[0:3], v107 offset:112
	s_waitcnt lgkmcnt(11)
	v_fma_f32 v12, -v93, v113, v12
	v_fma_f32 v4, v93, v112, v4
	v_fma_f32 v12, v92, v112, v12
	v_fma_f32 v4, v92, v113, v4
	v_fma_f32 v13, -v93, v4, v13
	v_fma_f32 v5, v93, v12, v5
	v_cvt_pk_bf16_f32 v112, v12, v4
	v_fma_f32 v113, v92, v12, v13
	v_fma_f32 v138, v92, v4, v5
	v_fma_f32 v4, -v93, v138, v14
	v_fma_f32 v5, v93, v113, v6
	v_fma_f32 v139, v92, v113, v4
	v_fma_f32 v140, v92, v138, v5
	v_cvt_pk_bf16_f32 v113, v113, v138
	v_add_u32_e32 v138, 0x4800, v108
	v_fma_f32 v141, -v93, v140, v15
	v_fma_f32 v142, v93, v139, v7
	ds_read_b128 v[12:15], v107 offset:9312
	ds_read_b128 v[4:7], v107 offset:9328
	ds_write2_b32 v138, v112, v113 offset1:68
	v_cvt_pk_bf16_f32 v112, v139, v140
	v_fma_f32 v113, v92, v139, v141
	v_fma_f32 v139, v92, v140, v142
	v_cvt_pk_bf16_f32 v140, v113, v139
	ds_write2_b32 v138, v112, v140 offset0:136 offset1:204
	s_waitcnt lgkmcnt(14)
	v_fma_f32 v112, -v93, v139, v118
	v_fma_f32 v114, v93, v113, v114
	v_fma_f32 v112, v92, v113, v112
	v_fma_f32 v113, v92, v139, v114
	v_fma_f32 v118, -v93, v113, v119
	v_fma_f32 v115, v93, v112, v115
	v_cvt_pk_bf16_f32 v114, v112, v113
	v_fma_f32 v112, v92, v112, v118
	v_fma_f32 v113, v92, v113, v115
	v_add_u32_e32 v118, 0x4c00, v108
	v_cvt_pk_bf16_f32 v115, v112, v113
	ds_write2_b32 v118, v114, v115 offset0:16 offset1:84
	v_fma_f32 v115, v93, v112, v116
	v_fma_f32 v114, -v93, v113, v120
	v_fma_f32 v112, v92, v112, v114
	v_fma_f32 v113, v92, v113, v115
	v_fma_f32 v115, -v93, v113, v121
	v_cvt_pk_bf16_f32 v114, v112, v113
	v_fma_f32 v116, v93, v112, v117
	v_fma_f32 v112, v92, v112, v115
	v_fma_f32 v113, v92, v113, v116
	v_cvt_pk_bf16_f32 v115, v112, v113
	ds_write2_b32 v118, v114, v115 offset0:152 offset1:220
	s_waitcnt lgkmcnt(13)
	v_fma_f32 v115, v93, v112, v130
	v_fma_f32 v114, -v93, v113, v122
	v_fma_f32 v112, v92, v112, v114
	v_fma_f32 v113, v92, v113, v115
	v_fma_f32 v115, -v93, v113, v123
	v_fma_f32 v116, v93, v112, v131
	v_cvt_pk_bf16_f32 v114, v112, v113
	v_fma_f32 v112, v92, v112, v115
	v_fma_f32 v113, v92, v113, v116
	v_add_u32_e32 v116, 0x5000, v108
	v_cvt_pk_bf16_f32 v115, v112, v113
	ds_write2_b32 v116, v114, v115 offset0:32 offset1:100
	v_fma_f32 v115, v93, v112, v132
	v_fma_f32 v114, -v93, v113, v124
	v_fma_f32 v112, v92, v112, v114
	v_fma_f32 v113, v92, v113, v115
	v_fma_f32 v115, -v93, v113, v125
	v_cvt_pk_bf16_f32 v114, v112, v113
	v_fma_f32 v117, v93, v112, v133
	v_fma_f32 v112, v92, v112, v115
	v_fma_f32 v113, v92, v113, v117
	v_cvt_pk_bf16_f32 v115, v112, v113
	ds_write2_b32 v116, v114, v115 offset0:168 offset1:236
	s_waitcnt lgkmcnt(14)
	v_fma_f32 v115, v93, v112, v134
	v_fma_f32 v114, -v93, v113, v126
	v_fma_f32 v112, v92, v112, v114
	v_fma_f32 v113, v92, v113, v115
	v_fma_f32 v115, -v93, v113, v127
	v_fma_f32 v116, v93, v112, v135
	v_cvt_pk_bf16_f32 v114, v112, v113
	v_fma_f32 v112, v92, v112, v115
	v_fma_f32 v113, v92, v113, v116
	v_add_u32_e32 v116, 0x5400, v108
	v_cvt_pk_bf16_f32 v115, v112, v113
	ds_write2_b32 v116, v114, v115 offset0:48 offset1:116
	v_fma_f32 v114, -v93, v113, v128
	v_fma_f32 v115, v93, v112, v136
	v_fma_f32 v112, v92, v112, v114
	v_fma_f32 v113, v92, v113, v115
	v_cvt_pk_bf16_f32 v114, v112, v113
	v_fma_f32 v115, -v93, v113, v129
	v_fma_f32 v117, v93, v112, v137
	v_fma_f32 v112, v92, v112, v115
	v_fma_f32 v113, v92, v113, v117
	s_waitcnt lgkmcnt(14)
	v_fma_f32 v28, -v93, v113, v28
	s_waitcnt lgkmcnt(12)
	v_fma_f32 v24, v93, v112, v24
	v_cvt_pk_bf16_f32 v115, v112, v113
	v_fma_f32 v28, v92, v112, v28
	v_fma_f32 v24, v92, v113, v24
	ds_write2_b32 v116, v114, v115 offset0:184 offset1:252
	v_fma_f32 v29, -v93, v24, v29
	v_fma_f32 v25, v93, v28, v25
	v_cvt_pk_bf16_f32 v112, v28, v24
	v_fma_f32 v28, v92, v28, v29
	v_fma_f32 v24, v92, v24, v25
	v_add_u32_e32 v29, 0x5800, v108
	v_cvt_pk_bf16_f32 v25, v28, v24
	ds_write2_b32 v29, v112, v25 offset0:64 offset1:132
	v_fma_f32 v25, -v93, v24, v30
	v_fma_f32 v26, v93, v28, v26
	v_fma_f32 v25, v92, v28, v25
	v_fma_f32 v24, v92, v24, v26
	v_cvt_pk_bf16_f32 v26, v25, v24
	v_fma_f32 v28, -v93, v24, v31
	v_fma_f32 v27, v93, v25, v27
	v_fma_f32 v25, v92, v25, v28
	v_fma_f32 v24, v92, v24, v27
	v_add_u32_e32 v28, 0x5a00, v108
	v_fma_f32 v20, -v93, v24, v20
	s_waitcnt lgkmcnt(13)
	v_fma_f32 v16, v93, v25, v16
	v_cvt_pk_bf16_f32 v27, v25, v24
	v_fma_f32 v20, v92, v25, v20
	v_fma_f32 v16, v92, v24, v16
	ds_write2_b32 v28, v26, v27 offset0:72 offset1:140
	v_fma_f32 v21, -v93, v16, v21
	v_fma_f32 v17, v93, v20, v17
	v_cvt_pk_bf16_f32 v24, v20, v16
	v_fma_f32 v20, v92, v20, v21
	v_fma_f32 v16, v92, v16, v17
	v_add_u32_e32 v21, 0x5c00, v108
	v_cvt_pk_bf16_f32 v17, v20, v16
	ds_write2_b32 v21, v24, v17 offset0:80 offset1:148
	v_fma_f32 v17, -v93, v16, v22
	v_fma_f32 v18, v93, v20, v18
	v_fma_f32 v17, v92, v20, v17
	v_fma_f32 v16, v92, v16, v18
	v_cvt_pk_bf16_f32 v18, v17, v16
	v_fma_f32 v20, -v93, v16, v23
	v_fma_f32 v19, v93, v17, v19
	v_fma_f32 v17, v92, v17, v20
	v_fma_f32 v16, v92, v16, v19
	v_add_u32_e32 v20, 0x5e00, v108
	s_waitcnt lgkmcnt(14)
	v_fma_f32 v8, -v93, v16, v8
	s_waitcnt lgkmcnt(12)
	v_fma_f32 v12, v93, v17, v12
	v_cvt_pk_bf16_f32 v19, v17, v16
	v_fma_f32 v8, v92, v17, v8
	v_fma_f32 v12, v92, v16, v12
	ds_write2_b32 v20, v18, v19 offset0:88 offset1:156
	v_fma_f32 v9, -v93, v12, v9
	v_fma_f32 v13, v93, v8, v13
	v_cvt_pk_bf16_f32 v16, v8, v12
	v_fma_f32 v8, v92, v8, v9
	v_fma_f32 v9, v92, v12, v13
	v_add_u32_e32 v13, 0x6000, v108
	v_cvt_pk_bf16_f32 v12, v8, v9
	ds_write2_b32 v13, v16, v12 offset0:96 offset1:164
	v_fma_f32 v10, -v93, v9, v10
	v_fma_f32 v12, v93, v8, v14
	v_fma_f32 v8, v92, v8, v10
	v_fma_f32 v9, v92, v9, v12
	v_cvt_pk_bf16_f32 v10, v8, v9
	v_fma_f32 v11, -v93, v9, v11
	v_fma_f32 v12, v93, v8, v15
	v_fma_f32 v8, v92, v8, v11
	v_fma_f32 v9, v92, v9, v12
	v_add_u32_e32 v12, 0x6200, v108
	v_fma_f32 v0, -v93, v9, v0
	s_waitcnt lgkmcnt(13)
	v_fma_f32 v4, v93, v8, v4
	v_cvt_pk_bf16_f32 v11, v8, v9
	v_fma_f32 v0, v92, v8, v0
	v_fma_f32 v4, v92, v9, v4
	ds_write2_b32 v12, v10, v11 offset0:104 offset1:172
	v_fma_f32 v1, -v93, v4, v1
	v_fma_f32 v5, v93, v0, v5
	v_cvt_pk_bf16_f32 v8, v0, v4
	v_fma_f32 v0, v92, v0, v1
	v_fma_f32 v1, v92, v4, v5
	v_add_u32_e32 v5, 0x6400, v108
	v_cvt_pk_bf16_f32 v4, v0, v1
	ds_write2_b32 v5, v8, v4 offset0:112 offset1:180
	v_fma_f32 v2, -v93, v1, v2
	v_fma_f32 v4, v93, v0, v6
	v_fma_f32 v0, v92, v0, v2
	v_fma_f32 v1, v92, v1, v4
	v_cvt_pk_bf16_f32 v2, v0, v1
	v_fma_f32 v3, -v93, v1, v3
	v_fma_f32 v4, v93, v0, v7
	v_fma_f32 v112, v92, v0, v3
	v_fma_f32 v113, v92, v1, v4
	v_add_u32_e32 v1, 0x6600, v108
	v_cvt_pk_bf16_f32 v0, v112, v113
	ds_write2_b32 v1, v2, v0 offset0:120 offset1:188
	ds_read_b128 v[0:3], v103 offset:18432
	ds_read_b128 v[4:7], v103 offset:18496
	ds_read_b128 v[8:11], v103 offset:22784
	ds_read_b128 v[12:15], v103 offset:22848
	s_waitcnt lgkmcnt(3)
	v_mfma_f32_16x16x32_bf16 v[0:3], v[0:3], v[48:51], 0
	s_waitcnt lgkmcnt(1)
	v_mfma_f32_16x16x32_bf16 v[8:11], v[8:11], v[48:51], 0
	v_mfma_f32_16x16x32_bf16 v[0:3], v[4:7], v[52:55], v[0:3]
	s_waitcnt lgkmcnt(0)
	v_mfma_f32_16x16x32_bf16 v[4:7], v[12:15], v[52:55], v[8:11]
	s_nop 4
	ds_read_b128 v[8:11], v103 offset:18560
	ds_read_b128 v[12:15], v103 offset:18624
	s_waitcnt lgkmcnt(1)
	v_mfma_f32_16x16x32_bf16 v[0:3], v[8:11], v[56:59], v[0:3]
	ds_read_b128 v[8:11], v103 offset:22912
	ds_read_b128 v[16:19], v103 offset:22976
	s_waitcnt lgkmcnt(1)
	v_mfma_f32_16x16x32_bf16 v[4:7], v[8:11], v[56:59], v[4:7]
	v_add_u32_e32 v10, 0x6800, v109
	ds_read2_b32 v[8:9], v10 offset0:128 offset1:144
	v_mfma_f32_16x16x32_bf16 v[0:3], v[12:15], v[60:63], v[0:3]
	s_waitcnt lgkmcnt(1)
	v_mfma_f32_16x16x32_bf16 v[4:7], v[16:19], v[60:63], v[4:7]
	s_waitcnt lgkmcnt(0)
	s_nop 4
	v_pk_fma_f32 v[0:1], v[90:91], v[8:9], v[0:1]
	s_nop 0
	v_mul_f32_e32 v8, 0x3d372713, v0
	v_mul_f32_e32 v8, v0, v8
	v_fma_f32 v8, v0, v8, v0
	v_mul_f32_e32 v8, 0x3f4c422a, v8
	v_mul_f32_e32 v8, 0xc038aa3b, v8
	v_exp_f32_e32 v11, v8
	v_mul_f32_e32 v8, 0x3d372713, v1
	v_mul_f32_e32 v8, v1, v8
	v_fma_f32 v8, v1, v8, v1
	v_mul_f32_e32 v8, 0x3f4c422a, v8
	v_mul_f32_e32 v8, 0xc038aa3b, v8
	v_exp_f32_e32 v12, v8
	ds_read2_b32 v[8:9], v10 offset0:160 offset1:176
	v_add_f32_e32 v10, 1.0, v11
	v_rcp_f32_e32 v10, v10
	v_add_f32_e32 v11, 1.0, v12
	v_rcp_f32_e32 v11, v11
	s_waitcnt lgkmcnt(0)
	v_pk_fma_f32 v[2:3], v[90:91], v[8:9], v[2:3]
	v_add_u32_e32 v12, 0x6c00, v109
	v_mul_f32_e32 v8, 0x3d372713, v2
	v_mul_f32_e32 v9, 0x3d372713, v3
	v_mul_f32_e32 v8, v2, v8
	v_mul_f32_e32 v9, v3, v9
	v_fma_f32 v8, v2, v8, v2
	v_fma_f32 v9, v3, v9, v3
	v_mul_f32_e32 v8, 0x3f4c422a, v8
	v_mul_f32_e32 v9, 0x3f4c422a, v9
	v_mul_f32_e32 v8, 0xc038aa3b, v8
	v_mul_f32_e32 v9, 0xc038aa3b, v9
	v_exp_f32_e32 v8, v8
	v_exp_f32_e32 v9, v9
	v_pk_mul_f32 v[0:1], v[0:1], v[10:11]
	ds_read2_b32 v[10:11], v12 offset0:128 offset1:144
	v_add_f32_e32 v8, 1.0, v8
	v_add_f32_e32 v9, 1.0, v9
	v_rcp_f32_e32 v8, v8
	v_rcp_f32_e32 v9, v9
	s_nop 0
	v_pk_mul_f32 v[2:3], v[2:3], v[8:9]
	v_cvt_pk_bf16_f32 v8, v0, v1
	s_waitcnt lgkmcnt(0)
	v_pk_fma_f32 v[0:1], v[90:91], v[10:11], v[4:5]
	v_cvt_pk_bf16_f32 v9, v2, v3
	v_mul_f32_e32 v2, 0x3d372713, v0
	v_mul_f32_e32 v2, v0, v2
	v_fma_f32 v2, v0, v2, v0
	v_mul_f32_e32 v2, 0x3f4c422a, v2
	v_mul_f32_e32 v2, 0xc038aa3b, v2
	v_exp_f32_e32 v4, v2
	v_mul_f32_e32 v2, 0x3d372713, v1
	v_mul_f32_e32 v2, v1, v2
	v_fma_f32 v2, v1, v2, v1
	v_mul_f32_e32 v2, 0x3f4c422a, v2
	v_mul_f32_e32 v2, 0xc038aa3b, v2
	v_exp_f32_e32 v5, v2
	ds_read2_b32 v[2:3], v12 offset0:160 offset1:176
	v_add_f32_e32 v4, 1.0, v4
	v_rcp_f32_e32 v4, v4
	v_add_f32_e32 v5, 1.0, v5
	v_rcp_f32_e32 v5, v5
	s_waitcnt lgkmcnt(0)
	v_pk_fma_f32 v[2:3], v[90:91], v[2:3], v[6:7]
	ds_write_b16 v110, v8 offset:29184
	v_mul_f32_e32 v6, 0x3d372713, v2
	v_mul_f32_e32 v7, 0x3d372713, v3
	v_mul_f32_e32 v6, v2, v6
	v_mul_f32_e32 v7, v3, v7
	v_fma_f32 v6, v2, v6, v2
	v_fma_f32 v7, v3, v7, v3
	v_mul_f32_e32 v6, 0x3f4c422a, v6
	v_mul_f32_e32 v7, 0x3f4c422a, v7
	v_mul_f32_e32 v6, 0xc038aa3b, v6
	v_mul_f32_e32 v7, 0xc038aa3b, v7
	v_exp_f32_e32 v6, v6
	v_exp_f32_e32 v7, v7
	v_pk_mul_f32 v[0:1], v[0:1], v[4:5]
	ds_write_b16_d16_hi v110, v8 offset:29216
	v_add_f32_e32 v6, 1.0, v6
	v_add_f32_e32 v7, 1.0, v7
	v_rcp_f32_e32 v6, v6
	v_rcp_f32_e32 v7, v7
	v_cvt_pk_bf16_f32 v0, v0, v1
	ds_write_b16 v110, v9 offset:29248
	ds_write_b16_d16_hi v110, v9 offset:29280
	v_lshl_add_u64 v[4:5], v[96:97], 0, s[36:37]
	v_pk_mul_f32 v[2:3], v[2:3], v[6:7]
	s_add_u32 s36, s36, 0x10000
	v_cvt_pk_bf16_f32 v1, v2, v3
	ds_write_b16 v110, v0 offset:29696
	ds_write_b16_d16_hi v110, v0 offset:29728
	ds_write_b16 v110, v1 offset:29760
	ds_write_b16_d16_hi v110, v1 offset:29792
	ds_read_b128 v[0:3], v104 offset:29184
	s_addc_u32 s37, s37, 0
	s_cmp_eq_u32 s36, 0x400000
	s_waitcnt lgkmcnt(0)
	global_store_dwordx4 v[4:5], v[0:3], off
	s_nop 1
	v_mov_b64_e32 v[0:1], v[72:73]
	v_mov_b64_e32 v[2:3], v[74:75]
	v_mov_b32_e32 v4, v111
	s_cbranch_scc1 .LBB0_322
